# stack: compress tok loop prefetch + double-buffered LDS, ml_local gate loads before the barrier, permlane32_swap for the xor-32 max hop in sel
# speedup vs baseline: 1.0051x; 1.0051x over previous
; __device__ __forceinline__ float log_sigmoid(float x) { return fminf(x, 0.f) - log1pf(__expf(-fabsf(x))); }
; __device__ __forceinline__ void phase_ml_local(const Params& p, int layer, LAS unsigned char* lds, const bf16_t* Z, const float* G, float* CL, float* NL, float* GA, int tid, int wid, int lane) {
;     ...
;     for (int item = p.bid; item < 2048; item += p.gdim) {
;         const int bh = item >> 8, ck = item & 255, b = bh >> 2, hd = bh & 3, t0 = ck * 64, t = t0 + li;
;         u32x4 zk[4]; load_taps(Z, b, t, C_MLK + hd * 64 + d0, zk);
;         const u32x4 zv = *(const u32x4*)(Z + ((size_t)b * SEQ + t) * ZLD + C_MLV + hd * 64 + d0);
;         __syncthreads();
;         if (wid == 0) {
;             const size_t row = (size_t)b * SEQ + t0 + lane;
;             const float ig = G[row * 32 + hd] + bias[hd], lf = log_sigmoid(G[row * 32 + 4 + hd] + bias[4 + hd]);
;             const float bs = wave_incl_scan(lf, lane), gsum = __shfl(bs, 63), a = gsum - bs + ig, amax = wave_max(a);
;             wl[lane] = __expf(a - amax);
;             if (lane == 0) { GA[(bh * 256 + ck) * 2] = gsum; GA[(bh * 256 + ck) * 2 + 1] = amax; }
.LBB0_200:
	s_or_b64 exec, exec, s[50:51]
	v_ashrrev_i32_e32 v3, 31, v2
	v_lshl_add_u64 v[2:3], s[48:49], 0, v[2:3]
	v_mov_b64_e32 v[4:5], s[18:19]
	v_mad_u64_u32 v[4:5], s[50:51], v2, s59, v[4:5]
	v_mad_i32_i24 v5, v3, s59, v5
	s_lshl_b32 s26, s26, 1
	v_lshl_add_u64 v[2:3], v[4:5], 0, s[26:27]
	v_mov_b32_e32 v29, v1
	v_lshl_add_u64 v[2:3], v[2:3], 0, v[28:29]
	global_load_dwordx4 v[2:5], v[2:3], off offset:1024
	s_andn2_b64 vcc, exec, s[30:31]
	s_cbranch_vccnz .Lmll_nogate
	v_or_b32_e32 v0, s17, v23
	v_or_b32_e32 v30, s48, v0
	v_mov_b32_e32 v31, s49
	v_lshlrev_b64 v[30:31], 7, v[30:31]
	v_lshl_add_u64 v[30:31], s[20:21], 0, v[30:31]
	s_lshl_b32 s26, s15, 2
	v_lshl_add_u64 v[30:31], v[30:31], 0, s[26:27]
	v_mov_b32_e32 v29, s26
	global_load_dword v0, v[30:31], off
	global_load_dword v40, v29, s[24:25]
	s_nop 0
	global_load_dword v30, v[30:31], off offset:16
	s_nop 0
	global_load_dword v29, v29, s[24:25] offset:16
.Lmll_nogate:
	s_barrier
	s_cbranch_vccnz .LBB0_204
	s_mov_b32 s15, 0xbfb8aa3b
	s_waitcnt vmcnt(2)
	v_add_f32_e32 v0, v0, v40
	s_waitcnt vmcnt(0)
	v_add_f32_e32 v29, v30, v29
	v_min_f32_e32 v40, 0, v29
	v_mul_f32_e64 v29, |v29|, s15
	v_exp_f32_e32 v29, v29
	s_mov_b32 s15, 0x3f2aaaab
	v_add_f32_e32 v41, 1.0, v29
	v_add_f32_e32 v30, -1.0, v41
	v_sub_f32_e32 v31, v30, v41
	v_add_f32_e32 v31, 1.0, v31
	v_sub_f32_e32 v30, v29, v30
	v_add_f32_e32 v42, v30, v31
	v_frexp_mant_f32_e32 v30, v41
	v_cmp_gt_f32_e32 vcc, s15, v30
	v_cvt_f64_f32_e32 v[30:31], v41
	v_frexp_exp_i32_f64_e32 v30, v[30:31]
	v_subbrev_co_u32_e32 v30, vcc, 0, v30, vcc
	v_sub_u32_e32 v31, 0, v30
	v_ldexp_f32 v41, v41, v31
	v_ldexp_f32 v31, v42, v31
	v_add_f32_e32 v42, -1.0, v41
	v_add_f32_e32 v43, 1.0, v42
	v_sub_f32_e32 v43, v41, v43
	v_add_f32_e32 v43, v31, v43
	v_add_f32_e32 v44, v42, v43
	v_sub_f32_e32 v42, v44, v42
	v_sub_f32_e32 v42, v43, v42
	v_add_f32_e32 v43, 1.0, v41
	v_add_f32_e32 v45, -1.0, v43
	v_sub_f32_e32 v41, v41, v45
	v_add_f32_e32 v31, v31, v41
	v_add_f32_e32 v41, v43, v31
	v_sub_f32_e32 v43, v41, v43
	v_sub_f32_e32 v31, v31, v43
	v_rcp_f32_e32 v43, v41
	v_cvt_f32_i32_e32 v30, v30
	s_mov_b32 s15, 0x3f317218
	v_mul_f32_e32 v45, v44, v43
	v_mul_f32_e32 v46, v41, v45
	v_fma_f32 v47, v45, v41, -v46
	v_fmac_f32_e32 v47, v45, v31
	v_add_f32_e32 v48, v46, v47
	v_sub_f32_e32 v49, v44, v48
	v_sub_f32_e32 v44, v44, v49
	v_sub_f32_e32 v46, v48, v46
	v_sub_f32_e32 v44, v44, v48
	v_add_f32_e32 v42, v42, v44
	v_sub_f32_e32 v44, v46, v47
	v_add_f32_e32 v42, v44, v42
	v_add_f32_e32 v44, v49, v42
	v_mul_f32_e32 v46, v43, v44
	v_mul_f32_e32 v47, v41, v46
	v_fma_f32 v41, v46, v41, -v47
	v_fmac_f32_e32 v41, v46, v31
	v_sub_f32_e32 v31, v49, v44
	v_add_f32_e32 v31, v42, v31
	v_add_f32_e32 v42, v47, v41
	v_sub_f32_e32 v48, v44, v42
	v_sub_f32_e32 v44, v44, v48
	v_sub_f32_e32 v47, v42, v47
	v_sub_f32_e32 v42, v44, v42
	v_add_f32_e32 v31, v31, v42
	v_sub_f32_e32 v41, v47, v41
	v_add_f32_e32 v31, v41, v31
	v_add_f32_e32 v41, v45, v46
	v_add_f32_e32 v31, v48, v31
	v_sub_f32_e32 v42, v41, v45
	v_mul_f32_e32 v31, v43, v31
	v_sub_f32_e32 v42, v46, v42
	v_add_f32_e32 v31, v42, v31
	v_mul_f32_e32 v45, 0x3f317218, v30
	v_add_f32_e32 v42, v41, v31
	v_fma_f32 v46, v30, s15, -v45
	v_mul_f32_e32 v43, v42, v42
	v_fmac_f32_e32 v46, 0xb102e308, v30
	v_sub_f32_e32 v30, v42, v41
	v_fmamk_f32 v44, v43, 0x3e9b6dac, v240
	v_sub_f32_e32 v30, v31, v30
	v_add_f32_e32 v31, v45, v46
	v_fmaak_f32 v44, v43, v44, 0x3f2aaada
	v_sub_f32_e32 v41, v31, v45
	v_ldexp_f32 v45, v42, 1
	v_mul_f32_e32 v42, v42, v43
	v_mul_f32_e32 v42, v42, v44
	v_add_f32_e32 v43, v45, v42
	v_sub_f32_e32 v44, v43, v45
	v_ldexp_f32 v30, v30, 1
	v_sub_f32_e32 v42, v42, v44
	v_add_f32_e32 v30, v30, v42
	v_add_f32_e32 v42, v43, v30
	v_sub_f32_e32 v43, v42, v43
	v_sub_f32_e32 v30, v30, v43
	v_add_f32_e32 v43, v31, v42
	v_sub_f32_e32 v44, v43, v31
	v_sub_f32_e32 v45, v43, v44
	v_sub_f32_e32 v41, v46, v41
	v_sub_f32_e32 v31, v31, v45
	v_sub_f32_e32 v42, v42, v44
	v_add_f32_e32 v31, v42, v31
	v_add_f32_e32 v42, v41, v30
	v_sub_f32_e32 v44, v42, v41
	v_sub_f32_e32 v45, v42, v44
	v_sub_f32_e32 v41, v41, v45
	v_sub_f32_e32 v30, v30, v44
	v_add_f32_e32 v31, v42, v31
	v_add_f32_e32 v30, v30, v41
	v_add_f32_e32 v41, v43, v31
	v_sub_f32_e32 v42, v41, v43
	v_sub_f32_e32 v31, v31, v42
	v_add_f32_e32 v30, v30, v31
	s_mov_b32 s15, 0x7f800000
	v_add_f32_e32 v30, v41, v30
	v_cmp_neq_f32_e32 vcc, s15, v29
	s_mov_b32 s15, 0x33800000
	v_and_b32_e32 v31, 64, v244
	v_cndmask_b32_e32 v30, v250, v30, vcc
	v_cmp_ngt_f32_e32 vcc, -1.0, v29
	s_nop 1
	v_cndmask_b32_e32 v30, v242, v30, vcc
	v_cmp_neq_f32_e32 vcc, -1.0, v29
	s_nop 1
	v_cndmask_b32_e32 v30, v243, v30, vcc
	v_cmp_lt_f32_e64 vcc, |v29|, s15
	s_nop 1
	v_cndmask_b32_e32 v29, v30, v29, vcc
	v_add_u32_e32 v30, -1, v244
	v_cmp_lt_i32_e32 vcc, v30, v31
	v_sub_f32_e32 v29, v40, v29
	v_xor_b32_e32 v40, 2, v244
	v_cndmask_b32_e32 v30, v30, v244, vcc
	v_lshlrev_b32_e32 v30, 2, v30
	ds_bpermute_b32 v30, v30, v29
	s_waitcnt lgkmcnt(0)
; __device__ __forceinline__ float wave_incl_scan(float v, int lane) {
; #pragma unroll
;     for (int o = 1; o < 64; o <<= 1) { const float t = __shfl_up(v, o); if (lane >= o) v += t; }
;     return v;
; }
; __device__ __forceinline__ float wave_incl_scanmax(float v, int lane) {
; #pragma unroll
;     for (int o = 1; o < 64; o <<= 1) { const float t = __shfl_up(v, o); if (lane >= o) v = fmaxf(v, t); }
;     return v;
; }
; __device__ __forceinline__ void phase_ml_local(const Params& p, int layer, LAS unsigned char* lds, const bf16_t* Z, const float* G, float* CL, float* NL, float* GA, int tid, int wid, int lane) {
;     ...
;             const float bs = wave_incl_scan(lf, lane), gsum = __shfl(bs, 63), a = gsum - bs + ig, amax = wave_max(a);
;             wl[lane] = __expf(a - amax);
;             if (lane == 0) { GA[(bh * 256 + ck) * 2] = gsum; GA[(bh * 256 + ck) * 2 + 1] = amax; }
	v_add_f32_e32 v30, v29, v30
	v_cndmask_b32_e64 v29, v30, v29, s[2:3]
	v_add_u32_e32 v30, -2, v244
	v_cmp_lt_i32_e32 vcc, v30, v31
	s_nop 1
	v_cndmask_b32_e32 v30, v30, v244, vcc
	v_lshlrev_b32_e32 v30, 2, v30
	ds_bpermute_b32 v30, v30, v29
	s_waitcnt lgkmcnt(0)
	v_add_f32_e32 v30, v29, v30
	v_cndmask_b32_e64 v29, v30, v29, s[4:5]
	v_add_u32_e32 v30, -4, v244
	v_cmp_lt_i32_e32 vcc, v30, v31
	s_nop 1
	v_cndmask_b32_e32 v30, v30, v244, vcc
	v_lshlrev_b32_e32 v30, 2, v30
	ds_bpermute_b32 v30, v30, v29
	s_waitcnt lgkmcnt(0)
	v_add_f32_e32 v30, v29, v30
	v_cndmask_b32_e64 v29, v30, v29, s[6:7]
	v_add_u32_e32 v30, -8, v244
	v_cmp_lt_i32_e32 vcc, v30, v31
	s_nop 1
	v_cndmask_b32_e32 v30, v30, v244, vcc
	v_lshlrev_b32_e32 v30, 2, v30
	ds_bpermute_b32 v30, v30, v29
	s_waitcnt lgkmcnt(0)
	v_add_f32_e32 v30, v29, v30
	v_cndmask_b32_e64 v29, v30, v29, s[8:9]
	v_add_u32_e32 v30, -16, v244
	v_cmp_lt_i32_e32 vcc, v30, v31
	s_nop 1
	v_cndmask_b32_e32 v30, v30, v244, vcc
	v_lshlrev_b32_e32 v30, 2, v30
	ds_bpermute_b32 v30, v30, v29
	s_waitcnt lgkmcnt(0)
	v_add_f32_e32 v30, v29, v30
	v_cndmask_b32_e64 v29, v30, v29, s[10:11]
	v_subrev_u32_e32 v30, 32, v244
	v_cmp_lt_i32_e32 vcc, v30, v31
	s_nop 1
	v_cndmask_b32_e32 v30, v30, v244, vcc
	v_lshlrev_b32_e32 v30, 2, v30
	ds_bpermute_b32 v30, v30, v29
	s_waitcnt lgkmcnt(0)
	v_add_f32_e32 v30, v29, v30
	v_cndmask_b32_e64 v29, v30, v29, s[12:13]
	ds_bpermute_b32 v30, v241, v29
	s_waitcnt lgkmcnt(0)
	v_sub_f32_e32 v29, v30, v29
	v_add_f32_e32 v0, v0, v29
	v_add_u32_e32 v29, 64, v31
	v_xor_b32_e32 v31, 1, v244
	v_cmp_lt_i32_e32 vcc, v31, v29
	s_nop 1
	v_cndmask_b32_e32 v31, v244, v31, vcc
	v_lshlrev_b32_e32 v31, 2, v31
	ds_bpermute_b32 v31, v31, v0
	v_cmp_lt_i32_e32 vcc, v40, v29
	s_waitcnt lgkmcnt(0)
	v_max_f32_e32 v31, v31, v31
	v_cndmask_b32_e32 v40, v244, v40, vcc
	v_max_f32_e32 v31, v0, v31
	v_lshlrev_b32_e32 v40, 2, v40
	ds_bpermute_b32 v40, v40, v31
	s_waitcnt lgkmcnt(0)
	v_max_f32_e32 v40, v40, v40
	v_max_f32_e32 v31, v31, v40
	v_xor_b32_e32 v40, 4, v244
	v_cmp_lt_i32_e32 vcc, v40, v29
	s_nop 1
	v_cndmask_b32_e32 v40, v244, v40, vcc
	v_lshlrev_b32_e32 v40, 2, v40
	ds_bpermute_b32 v40, v40, v31
	s_waitcnt lgkmcnt(0)
	v_max_f32_e32 v40, v40, v40
	v_max_f32_e32 v31, v31, v40
	v_xor_b32_e32 v40, 8, v244
	v_cmp_lt_i32_e32 vcc, v40, v29
	s_nop 1
	v_cndmask_b32_e32 v40, v244, v40, vcc
	v_lshlrev_b32_e32 v40, 2, v40
	ds_bpermute_b32 v40, v40, v31
	s_waitcnt lgkmcnt(0)
	v_max_f32_e32 v40, v40, v40
	v_max_f32_e32 v31, v31, v40
	v_xor_b32_e32 v40, 16, v244
	v_cmp_lt_i32_e32 vcc, v40, v29
	s_nop 1
	v_cndmask_b32_e32 v40, v244, v40, vcc
	v_lshlrev_b32_e32 v40, 2, v40
	ds_bpermute_b32 v40, v40, v31
	s_waitcnt lgkmcnt(0)
	v_max_f32_e32 v40, v40, v40
	v_max_f32_e32 v31, v31, v40
	v_xor_b32_e32 v40, 32, v244
	v_cmp_lt_i32_e32 vcc, v40, v29
	s_nop 1
	v_cndmask_b32_e32 v29, v244, v40, vcc
	v_lshlrev_b32_e32 v29, 2, v29
	ds_bpermute_b32 v29, v29, v31
	s_waitcnt lgkmcnt(0)
	v_max_f32_e32 v29, v29, v29
	v_max_f32_e32 v31, v31, v29
	v_sub_f32_e32 v0, v0, v31
	v_mul_f32_e32 v0, 0x3fb8aa3b, v0
	v_exp_f32_e32 v0, v0
	ds_write_b32 v33, v0 offset:18432
	s_and_saveexec_b64 s[48:49], s[2:3]
	s_cbranch_execz .LBB0_203
	s_ashr_i32 s43, s42, 31
	s_lshl_b64 s[50:51], s[42:43], 2
	s_add_u32 s50, s29, s50
	s_addc_u32 s51, s68, s51
	global_store_dwordx2 v1, v[30:31], s[50:51]

; #define LAS __attribute__((address_space(3)))
; __device__ __forceinline__ void phase_compress(const Params& p, int layer, LAS unsigned char* lds, const bf16_t* Z, bf16_t* KC, int tid, int wid, int lane) {
;     ...
;     for (int item = p.bid; item < 256; item += p.gdim) {
;         const int kv = item >> 7, bg = (item >> 5) & 3, rt = item & 31, c0 = rt * 32, b = bg >> 1, g = bg & 1;
;         const bf16_t* src = Z + (size_t)b * SEQ * ZLD + (kv ? C_VC : C_KC) + g * 64;
;         const bf16_t* W1 = (const bf16_t*)(p.ws + WS_WC1) + (size_t)(layer * 2 + kv) * 256 * 2048;
;         const bf16_t* W2 = (const bf16_t*)(p.ws + WS_WC2) + (size_t)(layer * 2 + kv) * 64 * 256;
;         const int n = wid * 32 + r;
;         f32x16 acc;
; #pragma unroll
;         for (int i = 0; i < 16; ++i) acc[i] = 0.f;
;         for (int tok = 0; tok < 32; ++tok) {
;             bf16x8 bf[4];
; #pragma unroll
;             for (int ks = 0; ks < 4; ++ks) bf[ks] = *(const bf16x8*)(W1 + (size_t)n * 2048 + tok * 64 + 16 * ks + 8 * h);
;             u32x4 av = {0u, 0u, 0u, 0u};
;             if (tid < 256) { int token = 16 * (c0 + (tid >> 3)) + tok; token = token < SEQ ? token : SEQ - 1; av = *(const u32x4*)(src + (size_t)token * ZLD + (tid & 7) * 8); }
;             __syncthreads();
;     ...
;             { unsigned w[4] = {av.x, av.y, av.z, av.w};
;               for (int e = 0; e < 4; ++e) { if (((w[e] >> 7) & 0xffu) > 140u) w[e] &= 0xffff0000u; if (((w[e] >> 23) & 0xffu) > 140u) w[e] &= 0x0000ffffu; }
;               av.x = w[0]; av.y = w[1]; av.z = w[2]; av.w = w[3]; }
;     ...
;             if (tid < 256) *(LAS u32x4*)(As + (tid >> 3) * 72 + (tid & 7) * 8) = av;
;             __syncthreads();
; #pragma unroll
;             for (int ks = 0; ks < 4; ++ks) { const bf16x8 a = *(const LAS bf16x8*)(As + r * 72 + 16 * ks + 8 * h); acc = __builtin_amdgcn_mfma_f32_32x32x16_bf16(a, bf[ks], acc, 0, 0, 0); }
;         }
.LBB0_213:
	s_lshl_b32 s10, s17, 4
	s_and_b32 s10, s10, 0x3e00
	s_lshl_b32 s11, s14, 8
	v_add_u32_e32 v53, s10, v41
	s_ashr_i32 s10, s14, 7
	s_bfe_u32 s19, s14, 0x20005
	s_and_b32 s11, s11, 0x4000
	s_cmpk_lt_u32 s14, 0x80
	s_movk_i32 s12, 0x1200
	s_mulk_i32 s11, 0x1a00
	s_cselect_b32 s12, s12, 0x1300
	s_add_u32 s11, s4, s11
	s_addc_u32 s13, s5, 0
	s_add_u32 s11, s11, s12
	s_addc_u32 s13, s13, 0
	s_lshl_b32 s12, s14, 2
	s_and_b32 s12, s12, 0x80
	s_add_u32 s12, s11, s12
	s_addc_u32 s13, s13, 0
	s_ashr_i32 s11, s10, 31
	v_lshl_add_u64 v[80:81], s[12:13], 0, v[0:1]
	s_lshl_b64 s[12:13], s[10:11], 20
	v_mov_b32_e32 v2, 0
	s_mov_b32 s20, 0
	v_lshl_add_u64 v[82:83], v[78:79], 0, s[12:13]
	v_mov_b32_e32 v3, v2
	v_mov_b32_e32 v4, v2
	v_mov_b32_e32 v5, v2
	v_mov_b32_e32 v6, v2
	v_mov_b32_e32 v7, v2
	v_mov_b32_e32 v8, v2
	v_mov_b32_e32 v9, v2
	v_mov_b32_e32 v10, v2
	v_mov_b32_e32 v11, v2
	v_mov_b32_e32 v12, v2
	v_mov_b32_e32 v13, v2
	v_mov_b32_e32 v14, v2
	v_mov_b32_e32 v15, v2
	v_mov_b32_e32 v16, v2
	v_mov_b32_e32 v17, v2
	global_load_dwordx4 v[100:103], v[82:83], off offset:-128
	global_load_dwordx4 v[104:107], v[82:83], off offset:-96
	global_load_dwordx4 v[108:111], v[82:83], off offset:-64
	global_load_dwordx4 v[112:115], v[82:83], off offset:-32
	v_mov_b32_e32 v132, 0
	v_mov_b32_e32 v133, 0
	v_mov_b32_e32 v134, 0
	v_mov_b32_e32 v135, 0
	s_and_saveexec_b64 s[12:13], s[2:3]
	s_cbranch_execz .Lcmpr_noav_p
	v_add_u32_e32 v132, s20, v53
	v_min_i32_e32 v132, 0x3fff, v132
	v_mad_i64_i32 v[132:133], s[22:23], v132, s59, v[80:81]
	global_load_dwordx4 v[132:135], v[132:133], off
.Lcmpr_noav_p:
	s_or_b64 exec, exec, s[12:13]
	s_branch .LBB0_215
.LBB0_214:
.LBB0_215:
	v_add_u32_e32 v55, v43, v40
	global_load_dwordx4 v[116:119], v[82:83], off
	global_load_dwordx4 v[120:123], v[82:83], off offset:32
	global_load_dwordx4 v[124:127], v[82:83], off offset:64
	global_load_dwordx4 v[128:131], v[82:83], off offset:96
	v_mov_b32_e32 v136, 0
	v_mov_b32_e32 v137, 0
	v_mov_b32_e32 v138, 0
	v_mov_b32_e32 v139, 0
	s_and_saveexec_b64 s[12:13], s[2:3]
	s_cbranch_execz .Lcmpr_noav_o
	v_add3_u32 v136, v53, s20, 1
	v_min_i32_e32 v136, 0x3fff, v136
	v_mad_i64_i32 v[136:137], s[22:23], v136, s59, v[80:81]
	global_load_dwordx4 v[136:139], v[136:137], off
.Lcmpr_noav_o:
	s_or_b64 exec, exec, s[12:13]
	s_waitcnt vmcnt(4)
	s_and_saveexec_b64 s[12:13], s[2:3]
	ds_write_b128 v47, v[132:135]
	s_or_b64 exec, exec, s[12:13]
	s_waitcnt lgkmcnt(0)
	s_barrier
	ds_read_b128 v[140:143], v55
	ds_read_b128 v[144:147], v55 offset:32
	ds_read_b128 v[148:151], v55 offset:64
	ds_read_b128 v[152:155], v55 offset:96
	s_waitcnt lgkmcnt(3)
	v_mfma_f32_32x32x16_bf16 v[2:17], v[140:143], v[100:103], v[2:17]
	s_waitcnt lgkmcnt(2)
	v_mfma_f32_32x32x16_bf16 v[2:17], v[144:147], v[104:107], v[2:17]
	s_waitcnt lgkmcnt(1)
	v_mfma_f32_32x32x16_bf16 v[2:17], v[148:151], v[108:111], v[2:17]
	s_waitcnt lgkmcnt(0)
	v_mfma_f32_32x32x16_bf16 v[2:17], v[152:155], v[112:115], v[2:17]
	s_add_i32 s20, s20, 2
	s_mov_b64 s[12:13], 0x100
	v_lshl_add_u64 v[82:83], v[82:83], 0, s[12:13]
	s_cmp_eq_u32 s20, 32
	s_cbranch_scc1 .Lcmpr_last
	global_load_dwordx4 v[100:103], v[82:83], off offset:-128
	global_load_dwordx4 v[104:107], v[82:83], off offset:-96
	global_load_dwordx4 v[108:111], v[82:83], off offset:-64
	global_load_dwordx4 v[112:115], v[82:83], off offset:-32
	v_mov_b32_e32 v132, 0
	v_mov_b32_e32 v133, 0
	v_mov_b32_e32 v134, 0
	v_mov_b32_e32 v135, 0
	s_and_saveexec_b64 s[12:13], s[2:3]
	s_cbranch_execz .Lcmpr_noav_e
	v_add_u32_e32 v132, s20, v53
	v_min_i32_e32 v132, 0x3fff, v132
	v_mad_i64_i32 v[132:133], s[22:23], v132, s59, v[80:81]
	global_load_dwordx4 v[132:135], v[132:133], off
.Lcmpr_noav_e:
	s_or_b64 exec, exec, s[12:13]
	s_waitcnt vmcnt(4)
	s_branch .Lcmpr_join

; #define LAS __attribute__((address_space(3)))
; __device__ __forceinline__ void phase_compress(const Params& p, int layer, LAS unsigned char* lds, const bf16_t* Z, bf16_t* KC, int tid, int wid, int lane) {
;     ...
;         for (int tok = 0; tok < 32; ++tok) {
;             bf16x8 bf[4];
; #pragma unroll
;             for (int ks = 0; ks < 4; ++ks) bf[ks] = *(const bf16x8*)(W1 + (size_t)n * 2048 + tok * 64 + 16 * ks + 8 * h);
;             u32x4 av = {0u, 0u, 0u, 0u};
;             if (tid < 256) { int token = 16 * (c0 + (tid >> 3)) + tok; token = token < SEQ ? token : SEQ - 1; av = *(const u32x4*)(src + (size_t)token * ZLD + (tid & 7) * 8); }
;             __syncthreads();
;     ...
;             { unsigned w[4] = {av.x, av.y, av.z, av.w};
;               for (int e = 0; e < 4; ++e) { if (((w[e] >> 7) & 0xffu) > 140u) w[e] &= 0xffff0000u; if (((w[e] >> 23) & 0xffu) > 140u) w[e] &= 0x0000ffffu; }
;               av.x = w[0]; av.y = w[1]; av.z = w[2]; av.w = w[3]; }
;     ...
;             if (tid < 256) *(LAS u32x4*)(As + (tid >> 3) * 72 + (tid & 7) * 8) = av;
;             __syncthreads();
; #pragma unroll
;             for (int ks = 0; ks < 4; ++ks) { const bf16x8 a = *(const LAS bf16x8*)(As + r * 72 + 16 * ks + 8 * h); acc = __builtin_amdgcn_mfma_f32_32x32x16_bf16(a, bf[ks], acc, 0, 0, 0); }
;         }
.Lcmpr_join:
	s_and_saveexec_b64 s[12:13], s[2:3]
	ds_write_b128 v47, v[136:139] offset:24576
	s_or_b64 exec, exec, s[12:13]
	s_waitcnt lgkmcnt(0)
	s_barrier
	ds_read_b128 v[140:143], v55 offset:24576
	ds_read_b128 v[144:147], v55 offset:24608
	ds_read_b128 v[148:151], v55 offset:24640
	ds_read_b128 v[152:155], v55 offset:24672
	s_waitcnt lgkmcnt(3)
	v_mfma_f32_32x32x16_bf16 v[2:17], v[140:143], v[116:119], v[2:17]
	s_waitcnt lgkmcnt(2)
	v_mfma_f32_32x32x16_bf16 v[2:17], v[144:147], v[120:123], v[2:17]
	s_waitcnt lgkmcnt(1)
	v_mfma_f32_32x32x16_bf16 v[2:17], v[148:151], v[124:127], v[2:17]
	s_waitcnt lgkmcnt(0)
	s_cmp_eq_u32 s20, 32
	v_mfma_f32_32x32x16_bf16 v[2:17], v[152:155], v[128:131], v[2:17]
	s_cbranch_scc1 .LBB0_223
	s_branch .LBB0_215

; __device__ __forceinline__ float ex2(float x) { return __builtin_amdgcn_exp2f(x); }
; __device__ __forceinline__ void sel_compute2(float& m, float& l, f32x4 (&o)[4], const long (&qf)[2], const SelBuf& A, const SelBuf& B, int kbA, int kbB, bool diagA, bool diagB, bool validB, int t, float c, int q4) {
;     ...
;     float mt = s[0][0];
; #pragma unroll
;     for (int ht = 0; ht < 8; ++ht)
; #pragma unroll
;         for (int e = 0; e < 4; ++e) mt = fmaxf(mt, s[ht][e]);
;     mt = fmaxf(mt, __shfl_xor(mt, 16)); mt = fmaxf(mt, __shfl_xor(mt, 32));
;     const float mn = fmaxf(m, mt);
;     float alpha = 1.f;
;     if (__any(mn != m)) {
;         alpha = ex2((m - mn) * c);
; #pragma unroll
;         for (int d = 0; d < 4; ++d) o[d] = o[d] * alpha;
;     }
.LBB0_713:
	s_or_b64 exec, exec, s[16:17]
	s_nop 1
	v_max_f32_e32 v182, v171, v171
	v_max_f32_e32 v183, v170, v170
	v_max_f32_e32 v182, v183, v182
	v_max3_f32 v182, v182, v172, v173
	v_max3_f32 v182, v182, v166, v167
	v_max3_f32 v182, v182, v168, v169
	v_max3_f32 v182, v182, v162, v163
	v_max3_f32 v182, v182, v164, v165
	v_max3_f32 v182, v182, v174, v175
	v_max3_f32 v182, v182, v176, v177
	v_max3_f32 v182, v182, v150, v151
	v_max3_f32 v182, v182, v152, v153
	v_max3_f32 v182, v182, v146, v147
	v_max3_f32 v182, v182, v148, v149
	v_max3_f32 v182, v182, v154, v155
	v_max3_f32 v182, v182, v156, v157
	v_max3_f32 v182, v182, v158, v159
	v_max3_f32 v182, v182, v160, v161
	ds_bpermute_b32 v183, v233, v182
	s_waitcnt lgkmcnt(0)
	v_max_f32_e32 v183, v183, v183
	v_max_f32_e32 v182, v182, v183
	v_mov_b32_e32 v183, v182
	v_mov_b32_e32 v184, v182
	s_nop 1
	v_permlane32_swap_b32_e32 v183, v184
	v_max3_f32 v214, v0, v183, v184
	v_cmp_neq_f32_e32 vcc, v214, v0
	s_cbranch_vccz .LBB0_715
	v_sub_f32_e32 v0, v0, v214
	v_mul_f32_e32 v0, 0x3e38aa3b, v0
	v_exp_f32_e32 v0, v0
	s_nop 0
	v_pk_mul_f32 v[100:101], v[100:101], v[0:1] op_sel_hi:[1,0]
	v_pk_mul_f32 v[98:99], v[98:99], v[0:1] op_sel_hi:[1,0]
	v_pk_mul_f32 v[112:113], v[112:113], v[0:1] op_sel_hi:[1,0]
	v_pk_mul_f32 v[110:111], v[110:111], v[0:1] op_sel_hi:[1,0]
	v_pk_mul_f32 v[140:141], v[140:141], v[0:1] op_sel_hi:[1,0]
	v_pk_mul_f32 v[138:139], v[138:139], v[0:1] op_sel_hi:[1,0]
	v_pk_mul_f32 v[144:145], v[144:145], v[0:1] op_sel_hi:[1,0]
	v_pk_mul_f32 v[142:143], v[142:143], v[0:1] op_sel_hi:[1,0]
	s_branch .LBB0_716

; __device__ __forceinline__ float ex2(float x) { return __builtin_amdgcn_exp2f(x); }
; __device__ __forceinline__ void sel_compute2(float& m, float& l, f32x4 (&o)[4], const long (&qf)[2], const SelBuf& A, const SelBuf& B, int kbA, int kbB, bool diagA, bool diagB, bool validB, int t, float c, int q4) {
;     ...
;     float mt = s[0][0];
; #pragma unroll
;     for (int ht = 0; ht < 8; ++ht)
; #pragma unroll
;         for (int e = 0; e < 4; ++e) mt = fmaxf(mt, s[ht][e]);
;     mt = fmaxf(mt, __shfl_xor(mt, 16)); mt = fmaxf(mt, __shfl_xor(mt, 32));
;     const float mn = fmaxf(m, mt);
;     float alpha = 1.f;
;     if (__any(mn != m)) {
;         alpha = ex2((m - mn) * c);
; #pragma unroll
;         for (int d = 0; d < 4; ++d) o[d] = o[d] * alpha;
;     }
.LBB0_793:
	s_or_b64 exec, exec, s[18:19]
	v_max_f32_e32 v0, v175, v175
	s_nop 1
	v_max_f32_e32 v182, v174, v174
	v_max_f32_e32 v0, v182, v0
	v_max3_f32 v0, v0, v176, v177
	v_max3_f32 v0, v0, v170, v171
	v_max3_f32 v0, v0, v172, v173
	v_max3_f32 v0, v0, v166, v167
	v_max3_f32 v0, v0, v168, v169
	v_max3_f32 v0, v0, v162, v163
	v_max3_f32 v0, v0, v164, v165
	v_max3_f32 v0, v0, v154, v155
	v_max3_f32 v0, v0, v156, v157
	v_max3_f32 v0, v0, v146, v147
	v_max3_f32 v0, v0, v148, v149
	v_max3_f32 v0, v0, v150, v151
	v_max3_f32 v0, v0, v152, v153
	v_max3_f32 v0, v0, v158, v159
	v_max3_f32 v0, v0, v160, v161
	ds_bpermute_b32 v182, v233, v0
	s_waitcnt lgkmcnt(0)
	v_max_f32_e32 v182, v182, v182
	v_max_f32_e32 v0, v0, v182
	v_mov_b32_e32 v182, v0
	v_mov_b32_e32 v183, v0
	s_nop 1
	v_permlane32_swap_b32_e32 v182, v183
	v_max3_f32 v0, v214, v182, v183
	v_cmp_neq_f32_e32 vcc, v0, v214
	s_cbranch_vccz .LBB0_796
	v_sub_f32_e32 v182, v214, v0
	v_mul_f32_e32 v182, 0x3e38aa3b, v182
	v_exp_f32_e32 v216, v182
	s_nop 0
	v_pk_mul_f32 v[100:101], v[100:101], v[216:217] op_sel_hi:[1,0]
	v_pk_mul_f32 v[112:113], v[112:113], v[216:217] op_sel_hi:[1,0]
	v_pk_mul_f32 v[140:141], v[140:141], v[216:217] op_sel_hi:[1,0]
	v_pk_mul_f32 v[144:145], v[144:145], v[216:217] op_sel_hi:[1,0]
	v_pk_mul_f32 v[98:99], v[98:99], v[216:217] op_sel_hi:[1,0]
	v_pk_mul_f32 v[110:111], v[110:111], v[216:217] op_sel_hi:[1,0]
	v_pk_mul_f32 v[138:139], v[138:139], v[216:217] op_sel_hi:[1,0]
	v_pk_mul_f32 v[142:143], v[142:143], v[216:217] op_sel_hi:[1,0]
	s_branch .LBB0_797
